# v18 + P9 next-unit Q-fragment loads issued from the current unit's epilogue (stacked)
# speedup vs baseline: 1.0119x; 1.0011x over previous
; #define GAS __attribute__((address_space(1)))
; DI float bflo(unsigned u) { return __uint_as_float(u << 16); }
; DI float bfhi(unsigned u) { return __uint_as_float(u & 0xffff0000u); }
; DI void attn_store(const f32x16 (&O)[2], float l, const bf16_t* sg, bf16_t* og, size_t rowoff, int hh) {
;     const float lt = l + __shfl_xor(l, 32);
;     const float inv = 1.f / lt;
; #pragma unroll
;     for (int db = 0; db < 2; ++db) {
;         float o[16];
; #pragma unroll
;         for (int g = 0; g < 4; ++g) {
;             const size_t idx = rowoff + db * 32 + 8 * g + 4 * hh;
;             const u32x2 sv = *(const GAS u32x2*)(sg + idx);
;             o[4 * g] = O[db][4 * g] * inv * bflo(sv.x); o[4 * g + 1] = O[db][4 * g + 1] * inv * bfhi(sv.x);
;             o[4 * g + 2] = O[db][4 * g + 2] * inv * bflo(sv.y); o[4 * g + 3] = O[db][4 * g + 3] * inv * bfhi(sv.y);
;         }
;         store_bf16_row32(og + rowoff + db * 32, o, hh);
;     }
; }
; template <int MODE>
; DI void attn_b_phase(unsigned char* ws, unsigned char* lds, int tid) {
;     ...
;         bf16x8 qf[6];
; #pragma unroll
;         for (int ks = 0; ks < 6; ++ks) qf[ks] = *(const bf16x8*)(q1 + (size_t)(t0 + r) * 1536 + h * 96 + ks * 16 + hh * 8);
.LBB0_1070:
	s_and_b64 vcc, exec, s[8:9]
	s_cbranch_vccnz .LBB0_1065
	s_lshl_b32 s58, s10, 10
	s_add_i32 s62, s58, 0x4000
	s_add_i32 s60, s58, 0x2000
	s_ashr_i32 s59, s58, 31
	s_add_i32 s74, s58, 16
	s_ashr_i32 s63, s62, 31
	s_add_i32 s75, s58, 0x5c00
	s_cmp_lt_i32 s10, 7
	s_cselect_b64 s[10:11], -1, 0
	s_and_b64 s[12:13], s[10:11], exec
	s_cselect_b32 s18, s60, 0x7800
	s_cselect_b32 s64, s60, 0x3c00
	s_cselect_b32 s19, s75, 0x9c00
	s_ashr_i32 s65, s64, 31
	s_ashr_i32 s61, s60, 31
	v_mov_b32_e32 v153, s63
	v_or_b32_e32 v152, s62, v144
	s_mov_b32 s76, 0
	s_mov_b64 s[12:13], 0
	s_add_i32 s77, s18, 16
	s_add_i32 s78, s74, 0x7c00
	s_add_i32 s79, s19, 16
	s_add_i32 s80, s74, 0xa000
	s_mov_b32 s18, s2
	s_mov_b32 s98, 0
	s_branch .LBB0_1073
.LBB0_1072:
	ds_read_b128 v[0:3], v158 offset:49152
	ds_read_b128 v[4:7], v158 offset:49184
	v_lshlrev_b64 v[16:17], 11, v[154:155]
	v_lshl_or_b32 v16, s81, 7, v16
	v_lshl_add_u64 v[18:19], v[146:147], 0, v[16:17]
	s_waitcnt lgkmcnt(0)
	v_mfma_f32_32x32x16_bf16 v[48:63], v[0:3], v[128:131], v[48:63]
	ds_read_b128 v[0:3], v158 offset:53760
	ds_read_b128 v[8:11], v158 offset:53792
	global_load_dwordx2 v[20:21], v[18:19], off
	global_load_dwordx2 v[22:23], v[18:19], off offset:16
	global_load_dwordx2 v[24:25], v[18:19], off offset:32
	global_load_dwordx2 v[26:27], v[18:19], off offset:48
	s_add_i32 s76, s76, 1
	v_mfma_f32_32x32x16_bf16 v[48:63], v[4:7], v[132:135], v[48:63]
	s_waitcnt lgkmcnt(0)
	v_mfma_f32_32x32x16_bf16 v[32:47], v[0:3], v[128:131], v[32:47]
	ds_read_b128 v[0:3], v158 offset:53824
	ds_read_b128 v[4:7], v158 offset:49216
	ds_read_b128 v[12:15], v158 offset:49248
	v_mfma_f32_32x32x16_bf16 v[32:47], v[8:11], v[132:135], v[32:47]
	v_and_b32_e32 v8, 64, v163
	v_xor_b32_e32 v10, 32, v163
	v_add_u32_e32 v11, 64, v8
	v_cmp_lt_i32_e32 vcc, v10, v11
	global_load_dwordx2 v[8:9], v[18:19], off offset:64
	s_nop 0
	v_cndmask_b32_e32 v10, v163, v10, vcc
	v_lshlrev_b32_e32 v10, 2, v10
	ds_bpermute_b32 v28, v10, v151
	v_lshl_add_u64 v[10:11], v[148:149], 0, v[16:17]
	global_load_dwordx2 v[16:17], v[18:19], off offset:80
	s_waitcnt lgkmcnt(0)
	v_mfma_f32_32x32x16_bf16 v[48:63], v[4:7], v[136:139], v[48:63]
	ds_read_b128 v[4:7], v158 offset:53856
	v_add_f32_e32 v30, v151, v28
	global_load_dwordx2 v[28:29], v[18:19], off offset:96
	s_nop 0
	global_load_dwordx2 v[18:19], v[18:19], off offset:112
	v_div_scale_f32 v31, s[12:13], v30, v30, 1.0
	s_mul_i32 s12, s76, s1
	s_add_i32 s18, s12, s2
	v_mfma_f32_32x32x16_bf16 v[32:47], v[0:3], v[136:139], v[32:47]
	v_rcp_f32_e32 v0, v31
	v_div_scale_f32 v1, vcc, 1.0, v30, 1.0
	s_cmpk_gt_i32 s18, 0x3ff
	s_cbranch_scc1 .Lp9q_skip
	s_lshl_b32 s92, s76, 3
	s_or_b32 s93, s92, s3
	s_ashr_i32 s94, s18, 5
	s_and_b32 s95, s18, 31
	s_and_b64 s[100:101], s[20:21], exec
	s_cselect_b32 s94, s93, s94
	s_cselect_b32 s95, s26, s95
	s_lshl_b32 s93, s94, 9
	s_and_b32 s93, s93, 0xffffe000
	s_lshl_b32 s95, s95, 8
	s_add_i32 s93, s93, s95
	s_and_b32 s94, s94, 15
	v_add_u32_e32 v203, s93, v159
	v_mov_b64_e32 v[200:201], s[16:17]
	v_mad_i64_i32 v[200:201], s[100:101], v203, s69, v[200:201]
	s_mul_i32 s92, s94, 0xc0
	s_mov_b32 s93, 0
	v_lshl_add_u64 v[200:201], v[200:201], 0, s[92:93]
	v_mov_b32_e32 v151, v97
	v_lshl_add_u64 v[200:201], v[200:201], 0, v[150:151]
	global_load_dwordx4 v[104:107], v[200:201], off
	global_load_dwordx4 v[108:111], v[200:201], off offset:32
	global_load_dwordx4 v[112:115], v[200:201], off offset:64
	global_load_dwordx4 v[116:119], v[200:201], off offset:96
	global_load_dwordx4 v[120:123], v[200:201], off offset:128
	global_load_dwordx4 v[124:127], v[200:201], off offset:160
	s_mov_b32 s98, 1
.Lp9q_skip:
	v_fma_f32 v2, -v31, v0, 1.0
	v_fmac_f32_e32 v0, v2, v0
	v_mul_f32_e32 v2, v1, v0
	v_mfma_f32_32x32x16_bf16 v[48:63], v[12:15], v[140:143], v[48:63]
	v_fma_f32 v3, -v31, v2, v1
	v_fmac_f32_e32 v2, v3, v0
	v_fma_f32 v1, -v31, v2, v1
	v_div_fmas_f32 v0, v1, v0, v2
	v_div_fixup_f32 v12, v0, v30, 1.0
	s_mov_b64 s[12:13], s[66:67]
	s_nop 5
	v_pk_mul_f32 v[0:1], v[48:49], v[12:13] op_sel_hi:[1,0]
	s_waitcnt lgkmcnt(0)
	v_mfma_f32_32x32x16_bf16 v[32:47], v[4:7], v[140:143], v[32:47]
	v_mul_f32_e64 v2, v50, v12
	v_mul_f32_e64 v3, v51, v12
	v_mul_f32_e64 v4, v52, v12
	v_mul_f32_e64 v5, v53, v12
	v_mul_f32_e64 v6, v54, v12
	v_mul_f32_e64 v7, v55, v12
	v_pk_mul_f32 v[14:15], v[56:57], v[12:13] op_sel_hi:[1,0]
	v_pk_mul_f32 v[30:31], v[58:59], v[12:13] op_sel_hi:[1,0]
	v_pk_mul_f32 v[48:49], v[60:61], v[12:13] op_sel_hi:[1,0]
	v_pk_mul_f32 v[50:51], v[62:63], v[12:13] op_sel_hi:[1,0]
	s_cmp_eq_u32 s98, 1
	s_cbranch_scc1 .Lp9q_w6
	s_waitcnt vmcnt(0)
	s_branch .Lp9q_wd
; #define GAS __attribute__((address_space(1)))
; DI float bflo(unsigned u) { return __uint_as_float(u << 16); }
; DI float bfhi(unsigned u) { return __uint_as_float(u & 0xffff0000u); }
; DI void attn_store(const f32x16 (&O)[2], float l, const bf16_t* sg, bf16_t* og, size_t rowoff, int hh) {
;     ...
;     for (int db = 0; db < 2; ++db) {
;         float o[16];
; #pragma unroll
;         for (int g = 0; g < 4; ++g) {
;             const size_t idx = rowoff + db * 32 + 8 * g + 4 * hh;
;             const u32x2 sv = *(const GAS u32x2*)(sg + idx);
;             o[4 * g] = O[db][4 * g] * inv * bflo(sv.x); o[4 * g + 1] = O[db][4 * g + 1] * inv * bfhi(sv.x);
;             o[4 * g + 2] = O[db][4 * g + 2] * inv * bflo(sv.y); o[4 * g + 3] = O[db][4 * g + 3] * inv * bfhi(sv.y);
;         }
;         store_bf16_row32(og + rowoff + db * 32, o, hh);
;     }
; template <int MODE>
; DI void attn_b_phase(unsigned char* ws, unsigned char* lds, int tid) {
;     ...
;         const int u = blockIdx.x + it * gridDim.x;
;         if (u >= 1024) break;
;         int bh, qt;
;         if (gridDim.x == 256) { bh = it * 8 + (blockIdx.x & 7); qt = blockIdx.x >> 3; } else { bh = u >> 5; qt = u & 31; }
;         const int b = bh >> 4, h = bh & 15;
;         const int t0 = b * SEQ + qt * 256 + w * 32;
;         bf16x8 qf[6];
; #pragma unroll
;         for (int ks = 0; ks < 6; ++ks) qf[ks] = *(const bf16x8*)(q1 + (size_t)(t0 + r) * 1536 + h * 96 + ks * 16 + hh * 8);
.Lp9q_w6:
	s_waitcnt vmcnt(6)
.Lp9q_wd:
	v_lshlrev_b32_e32 v52, 16, v20
	v_and_b32_e32 v53, 0xffff0000, v20
	v_lshlrev_b32_e32 v20, 16, v21
	v_and_b32_e32 v21, 0xffff0000, v21
	v_lshlrev_b32_e32 v54, 16, v22
	v_and_b32_e32 v55, 0xffff0000, v22
	v_lshlrev_b32_e32 v22, 16, v23
	v_and_b32_e32 v23, 0xffff0000, v23
	v_pk_mul_f32 v[0:1], v[0:1], v[52:53]
	v_pk_mul_f32 v[2:3], v[2:3], v[20:21]
	v_pk_mul_f32 v[4:5], v[4:5], v[54:55]
	v_pk_mul_f32 v[6:7], v[6:7], v[22:23]
	v_lshlrev_b32_e32 v56, 16, v24
	v_and_b32_e32 v57, 0xffff0000, v24
	v_lshlrev_b32_e32 v24, 16, v25
	v_and_b32_e32 v25, 0xffff0000, v25
	v_lshlrev_b32_e32 v58, 16, v26
	v_and_b32_e32 v59, 0xffff0000, v26
	v_lshlrev_b32_e32 v26, 16, v27
	v_and_b32_e32 v27, 0xffff0000, v27
	v_cvt_pk_bf16_f32 v0, v0, v1
	v_cvt_pk_bf16_f32 v1, v2, v3
	v_cvt_pk_bf16_f32 v2, v4, v5
	v_cvt_pk_bf16_f32 v3, v6, v7
	v_pk_mul_f32 v[14:15], v[14:15], v[56:57]
	v_pk_mul_f32 v[20:21], v[30:31], v[24:25]
	v_pk_mul_f32 v[22:23], v[48:49], v[58:59]
	v_pk_mul_f32 v[24:25], v[50:51], v[26:27]
	v_permlane32_swap_b32_e32 v0, v2
	v_permlane32_swap_b32_e32 v1, v3
	global_store_dwordx4 v[10:11], v[0:3], off
	v_lshlrev_b32_e32 v4, 16, v9
	v_and_b32_e32 v5, 0xffff0000, v9
	v_cvt_pk_bf16_f32 v0, v14, v15
	v_cvt_pk_bf16_f32 v1, v20, v21
	v_cvt_pk_bf16_f32 v2, v22, v23
	v_cvt_pk_bf16_f32 v3, v24, v25
	s_nop 0
	v_permlane32_swap_b32_e32 v0, v2
	v_permlane32_swap_b32_e32 v1, v3
	global_store_dwordx4 v[10:11], v[0:3], off offset:32
	v_lshlrev_b32_e32 v6, 16, v16
	v_and_b32_e32 v7, 0xffff0000, v16
	v_pk_mul_f32 v[0:1], v[32:33], v[12:13] op_sel_hi:[1,0]
	v_lshlrev_b32_e32 v2, 16, v8
	v_and_b32_e32 v3, 0xffff0000, v8
	v_pk_mul_f32 v[0:1], v[0:1], v[2:3]
	v_pk_mul_f32 v[2:3], v[34:35], v[12:13] op_sel_hi:[1,0]
	v_lshlrev_b32_e32 v8, 16, v17
	v_pk_mul_f32 v[2:3], v[2:3], v[4:5]
	v_pk_mul_f32 v[4:5], v[36:37], v[12:13] op_sel_hi:[1,0]
	v_and_b32_e32 v9, 0xffff0000, v17
	v_pk_mul_f32 v[4:5], v[4:5], v[6:7]
	v_pk_mul_f32 v[6:7], v[38:39], v[12:13] op_sel_hi:[1,0]
	v_lshlrev_b32_e32 v14, 16, v28
	v_pk_mul_f32 v[6:7], v[6:7], v[8:9]
	v_pk_mul_f32 v[8:9], v[40:41], v[12:13] op_sel_hi:[1,0]
	v_and_b32_e32 v15, 0xffff0000, v28
	v_pk_mul_f32 v[8:9], v[8:9], v[14:15]
	v_pk_mul_f32 v[14:15], v[42:43], v[12:13] op_sel_hi:[1,0]
	v_lshlrev_b32_e32 v16, 16, v29
	v_and_b32_e32 v17, 0xffff0000, v29
	v_pk_mul_f32 v[14:15], v[14:15], v[16:17]
	v_pk_mul_f32 v[16:17], v[44:45], v[12:13] op_sel_hi:[1,0]
	v_lshlrev_b32_e32 v20, 16, v18
	v_and_b32_e32 v21, 0xffff0000, v18
	v_pk_mul_f32 v[12:13], v[46:47], v[12:13] op_sel_hi:[1,0]
	v_lshlrev_b32_e32 v18, 16, v19
	v_and_b32_e32 v19, 0xffff0000, v19
	v_cvt_pk_bf16_f32 v0, v0, v1
	v_cvt_pk_bf16_f32 v1, v2, v3
	v_cvt_pk_bf16_f32 v2, v4, v5
	v_cvt_pk_bf16_f32 v3, v6, v7
	v_pk_mul_f32 v[16:17], v[16:17], v[20:21]
	v_pk_mul_f32 v[12:13], v[12:13], v[18:19]
	v_permlane32_swap_b32_e32 v0, v2
	v_permlane32_swap_b32_e32 v1, v3
	global_store_dwordx4 v[10:11], v[0:3], off offset:64
	s_nop 1
	v_cvt_pk_bf16_f32 v0, v8, v9
	v_cvt_pk_bf16_f32 v1, v14, v15
	v_cvt_pk_bf16_f32 v2, v16, v17
	v_cvt_pk_bf16_f32 v3, v12, v13
	s_nop 0
	v_permlane32_swap_b32_e32 v0, v2
	v_permlane32_swap_b32_e32 v1, v3
	global_store_dwordx4 v[10:11], v[0:3], off offset:96
	s_cmpk_gt_i32 s18, 0x3ff
	s_barrier
	s_cbranch_scc1 .LBB0_1065
.LBB0_1073:
	s_lshl_b32 s38, s76, 3
	s_or_b32 s19, s38, s3
	s_ashr_i32 s36, s18, 5
	s_and_b32 s39, s18, 31
	s_and_b64 s[34:35], s[20:21], exec
	s_cselect_b32 s35, s19, s36
	s_cselect_b32 s34, s26, s39
	s_lshl_b32 s19, s35, 9
	s_and_b32 s19, s19, 0xffffe000
	s_lshl_b32 s34, s34, 8
	s_add_i32 s19, s19, s34
	s_and_b32 s81, s35, 15
	v_add_u32_e32 v154, s19, v159
	v_mov_b64_e32 v[0:1], s[16:17]
	v_mad_i64_i32 v[0:1], s[40:41], v154, s69, v[0:1]
	s_mul_i32 s36, s81, 0xc0
	v_lshl_add_u64 v[0:1], v[0:1], 0, s[36:37]
	v_mov_b32_e32 v151, v97
	v_lshl_add_u64 v[0:1], v[0:1], 0, v[150:151]
	s_cmp_eq_u32 s98, 1
	s_cbranch_scc1 .Lp9q_have
	flat_load_dwordx4 v[104:107], v[0:1]
	flat_load_dwordx4 v[108:111], v[0:1] offset:32
	flat_load_dwordx4 v[112:115], v[0:1] offset:64
	flat_load_dwordx4 v[116:119], v[0:1] offset:96
	flat_load_dwordx4 v[120:123], v[0:1] offset:128
	flat_load_dwordx4 v[124:127], v[0:1] offset:160
.Lp9q_have:
	s_mov_b32 s98, 0
	s_add_i32 s36, s18, s1
	s_cmpk_lt_i32 s36, 0x400
	s_cselect_b64 s[66:67], -1, 0
	s_cmpk_gt_i32 s36, 0x3ff
	s_mov_b32 s34, s35
	s_cbranch_scc1 .LBB0_1078
	s_mov_b64 s[18:19], -1
	s_and_b64 vcc, exec, s[22:23]
	s_cbranch_vccz .LBB0_1076
	s_ashr_i32 s34, s36, 5
	s_mov_b64 s[18:19], 0
